# prompt-attention k_nope normalisation hoisted out of the per-tile staging into one in-place pass over KV at the start of P4; staging copies raw chunks to LDS
# speedup vs baseline: 1.0025x; 1.0025x over previous
.LBB0_706:
	s_or_b64 exec, exec, s[0:1]
	s_waitcnt vmcnt(0) lgkmcnt(0)
	v_mov_b32_e32 v2, v0
	s_barrier
	s_nop 0
	s_mov_b64 exec, -1
	v_readlane_b32 s12, v254, 40
	v_readlane_b32 s13, v254, 41
	v_readlane_b32 s14, v253, 40
	v_readlane_b32 s15, v253, 41
	v_and_b32_e32 v100, 63, v0
	v_lshrrev_b32_e32 v101, 6, v0
	v_and_b32_e32 v102, 7, v100
	v_lshrrev_b32_e32 v103, 3, v100
	v_lshlrev_b32_e32 v104, 5, v102
	v_lshlrev_b32_e32 v105, 4, v102
	v_lshl_add_u32 v105, v103, 8, v105
	v_readfirstlane_b32 s16, v101
	s_nop 3
	s_add_i32 s16, s97, s16
	s_lshl_b32 s17, s33, 3
	v_mov_b32_e32 v114, 0x358637bd
	s_waitcnt lgkmcnt(0)
	global_load_dwordx4 v[106:109], v104, s[14:15]
	global_load_dwordx4 v[110:113], v104, s[14:15] offset:16
	s_waitcnt vmcnt(0)
.Lkn_loop:
	s_cmp_ge_u32 s16, 0x8000
	s_cbranch_scc1 .Lkn_done
	s_mov_b32 s14, s16
	s_cmp_ge_u32 s14, 0x8000
	s_cbranch_scc1 .Lkn_ld_end
	v_mov_b32_e32 v152, s14
	v_lshl_add_u32 v152, v152, 11, v105
	global_load_dwordx4 v[120:123], v152, s[12:13]
	s_add_u32 s14, s14, s17
	s_cmp_ge_u32 s14, 0x8000
	s_cbranch_scc1 .Lkn_ld_end
	v_mov_b32_e32 v153, s14
	v_lshl_add_u32 v153, v153, 11, v105
	global_load_dwordx4 v[124:127], v153, s[12:13]
	s_add_u32 s14, s14, s17
	s_cmp_ge_u32 s14, 0x8000
	s_cbranch_scc1 .Lkn_ld_end
	v_mov_b32_e32 v154, s14
	v_lshl_add_u32 v154, v154, 11, v105
	global_load_dwordx4 v[128:131], v154, s[12:13]
	s_add_u32 s14, s14, s17
	s_cmp_ge_u32 s14, 0x8000
	s_cbranch_scc1 .Lkn_ld_end
	v_mov_b32_e32 v155, s14
	v_lshl_add_u32 v155, v155, 11, v105
	global_load_dwordx4 v[132:135], v155, s[12:13]
	s_add_u32 s14, s14, s17
	s_cmp_ge_u32 s14, 0x8000
	s_cbranch_scc1 .Lkn_ld_end
	v_mov_b32_e32 v156, s14
	v_lshl_add_u32 v156, v156, 11, v105
	global_load_dwordx4 v[136:139], v156, s[12:13]
	s_add_u32 s14, s14, s17
	s_cmp_ge_u32 s14, 0x8000
	s_cbranch_scc1 .Lkn_ld_end
	v_mov_b32_e32 v157, s14
	v_lshl_add_u32 v157, v157, 11, v105
	global_load_dwordx4 v[140:143], v157, s[12:13]
	s_add_u32 s14, s14, s17
	s_cmp_ge_u32 s14, 0x8000
	s_cbranch_scc1 .Lkn_ld_end
	v_mov_b32_e32 v158, s14
	v_lshl_add_u32 v158, v158, 11, v105
	global_load_dwordx4 v[144:147], v158, s[12:13]
	s_add_u32 s14, s14, s17
	s_cmp_ge_u32 s14, 0x8000
	s_cbranch_scc1 .Lkn_ld_end
	v_mov_b32_e32 v159, s14
	v_lshl_add_u32 v159, v159, 11, v105
	global_load_dwordx4 v[148:151], v159, s[12:13]
	s_add_u32 s14, s14, s17
.Lkn_ld_end:
	s_waitcnt vmcnt(0)
	s_mov_b32 s14, s16
	s_cmp_ge_u32 s14, 0x8000
	s_cbranch_scc1 .Lkn_st_end
	v_lshlrev_b32_e32 v160, 16, v120
	v_and_b32_e32 v161, 0xffff0000, v120
	v_lshlrev_b32_e32 v162, 16, v121
	v_and_b32_e32 v163, 0xffff0000, v121
	v_lshlrev_b32_e32 v164, 16, v122
	v_and_b32_e32 v165, 0xffff0000, v122
	v_lshlrev_b32_e32 v166, 16, v123
	v_and_b32_e32 v167, 0xffff0000, v123
	v_pk_mul_f32 v[168:169], v[160:161], v[160:161]
	v_pk_mul_f32 v[170:171], v[162:163], v[162:163]
	v_pk_mul_f32 v[172:173], v[164:165], v[164:165]
	v_pk_mul_f32 v[174:175], v[166:167], v[166:167]
	v_add_f32_e32 v168, v168, v169
	v_add_f32_e32 v168, v170, v168
	v_add_f32_e32 v168, v171, v168
	v_add_f32_e32 v168, v172, v168
	v_add_f32_e32 v168, v173, v168
	v_add_f32_e32 v168, v174, v168
	v_add_f32_e32 v168, v175, v168
	s_nop 1
	v_add_f32_dpp v168, v168, v168 quad_perm:[1,0,3,2] row_mask:0xf bank_mask:0xf
	s_nop 1
	v_add_f32_dpp v168, v168, v168 quad_perm:[2,3,0,1] row_mask:0xf bank_mask:0xf
	s_nop 1
	v_mov_b32_dpp v169, v168 row_half_mirror row_mask:0xf bank_mask:0xf
	v_add_f32_e32 v168, v168, v169
	v_fmamk_f32 v168, v168, 0x3c800000, v114
	v_rsq_f32_e32 v168, v168
	s_nop 0
	v_mul_f32_e32 v160, v168, v160
	v_mul_f32_e32 v161, v168, v161
	v_mul_f32_e32 v162, v168, v162
	v_mul_f32_e32 v163, v168, v163
	v_mul_f32_e32 v164, v168, v164
	v_mul_f32_e32 v165, v168, v165
	v_mul_f32_e32 v166, v168, v166
	v_mul_f32_e32 v167, v168, v167
	v_mul_f32_e32 v160, v106, v160
	v_mul_f32_e32 v161, v107, v161
	v_mul_f32_e32 v162, v108, v162
	v_mul_f32_e32 v163, v109, v163
	v_mul_f32_e32 v164, v110, v164
	v_mul_f32_e32 v165, v111, v165
	v_mul_f32_e32 v166, v112, v166
	v_mul_f32_e32 v167, v113, v167
	v_cvt_pk_bf16_f32 v120, v160, v161
	v_cvt_pk_bf16_f32 v121, v162, v163
	v_cvt_pk_bf16_f32 v122, v164, v165
	v_cvt_pk_bf16_f32 v123, v166, v167
	global_store_dwordx4 v152, v[120:123], s[12:13]
	s_add_u32 s14, s14, s17
	s_cmp_ge_u32 s14, 0x8000
	s_cbranch_scc1 .Lkn_st_end
	v_lshlrev_b32_e32 v160, 16, v124
	v_and_b32_e32 v161, 0xffff0000, v124
	v_lshlrev_b32_e32 v162, 16, v125
	v_and_b32_e32 v163, 0xffff0000, v125
	v_lshlrev_b32_e32 v164, 16, v126
	v_and_b32_e32 v165, 0xffff0000, v126
	v_lshlrev_b32_e32 v166, 16, v127
	v_and_b32_e32 v167, 0xffff0000, v127
	v_pk_mul_f32 v[168:169], v[160:161], v[160:161]
	v_pk_mul_f32 v[170:171], v[162:163], v[162:163]
	v_pk_mul_f32 v[172:173], v[164:165], v[164:165]
	v_pk_mul_f32 v[174:175], v[166:167], v[166:167]
	v_add_f32_e32 v168, v168, v169
	v_add_f32_e32 v168, v170, v168
	v_add_f32_e32 v168, v171, v168
	v_add_f32_e32 v168, v172, v168
	v_add_f32_e32 v168, v173, v168
	v_add_f32_e32 v168, v174, v168
	v_add_f32_e32 v168, v175, v168
	s_nop 1
	v_add_f32_dpp v168, v168, v168 quad_perm:[1,0,3,2] row_mask:0xf bank_mask:0xf
	s_nop 1
	v_add_f32_dpp v168, v168, v168 quad_perm:[2,3,0,1] row_mask:0xf bank_mask:0xf
	s_nop 1
	v_mov_b32_dpp v169, v168 row_half_mirror row_mask:0xf bank_mask:0xf
	v_add_f32_e32 v168, v168, v169
	v_fmamk_f32 v168, v168, 0x3c800000, v114
	v_rsq_f32_e32 v168, v168
	s_nop 0
	v_mul_f32_e32 v160, v168, v160
	v_mul_f32_e32 v161, v168, v161
	v_mul_f32_e32 v162, v168, v162
	v_mul_f32_e32 v163, v168, v163
	v_mul_f32_e32 v164, v168, v164
	v_mul_f32_e32 v165, v168, v165
	v_mul_f32_e32 v166, v168, v166
	v_mul_f32_e32 v167, v168, v167
	v_mul_f32_e32 v160, v106, v160
	v_mul_f32_e32 v161, v107, v161
	v_mul_f32_e32 v162, v108, v162
	v_mul_f32_e32 v163, v109, v163
	v_mul_f32_e32 v164, v110, v164
	v_mul_f32_e32 v165, v111, v165
	v_mul_f32_e32 v166, v112, v166
	v_mul_f32_e32 v167, v113, v167
	v_cvt_pk_bf16_f32 v124, v160, v161
	v_cvt_pk_bf16_f32 v125, v162, v163
	v_cvt_pk_bf16_f32 v126, v164, v165
	v_cvt_pk_bf16_f32 v127, v166, v167
	global_store_dwordx4 v153, v[124:127], s[12:13]
	s_add_u32 s14, s14, s17
	s_cmp_ge_u32 s14, 0x8000
	s_cbranch_scc1 .Lkn_st_end
	v_lshlrev_b32_e32 v160, 16, v128
	v_and_b32_e32 v161, 0xffff0000, v128
	v_lshlrev_b32_e32 v162, 16, v129
	v_and_b32_e32 v163, 0xffff0000, v129
	v_lshlrev_b32_e32 v164, 16, v130
	v_and_b32_e32 v165, 0xffff0000, v130
	v_lshlrev_b32_e32 v166, 16, v131
	v_and_b32_e32 v167, 0xffff0000, v131
	v_pk_mul_f32 v[168:169], v[160:161], v[160:161]
	v_pk_mul_f32 v[170:171], v[162:163], v[162:163]
	v_pk_mul_f32 v[172:173], v[164:165], v[164:165]
	v_pk_mul_f32 v[174:175], v[166:167], v[166:167]
	v_add_f32_e32 v168, v168, v169
	v_add_f32_e32 v168, v170, v168
	v_add_f32_e32 v168, v171, v168
	v_add_f32_e32 v168, v172, v168
	v_add_f32_e32 v168, v173, v168
	v_add_f32_e32 v168, v174, v168
	v_add_f32_e32 v168, v175, v168
	s_nop 1
	v_add_f32_dpp v168, v168, v168 quad_perm:[1,0,3,2] row_mask:0xf bank_mask:0xf
	s_nop 1
	v_add_f32_dpp v168, v168, v168 quad_perm:[2,3,0,1] row_mask:0xf bank_mask:0xf
	s_nop 1
	v_mov_b32_dpp v169, v168 row_half_mirror row_mask:0xf bank_mask:0xf
	v_add_f32_e32 v168, v168, v169
	v_fmamk_f32 v168, v168, 0x3c800000, v114
	v_rsq_f32_e32 v168, v168
	s_nop 0
	v_mul_f32_e32 v160, v168, v160
	v_mul_f32_e32 v161, v168, v161
	v_mul_f32_e32 v162, v168, v162
	v_mul_f32_e32 v163, v168, v163
	v_mul_f32_e32 v164, v168, v164
	v_mul_f32_e32 v165, v168, v165
	v_mul_f32_e32 v166, v168, v166
	v_mul_f32_e32 v167, v168, v167
	v_mul_f32_e32 v160, v106, v160
	v_mul_f32_e32 v161, v107, v161
	v_mul_f32_e32 v162, v108, v162
	v_mul_f32_e32 v163, v109, v163
	v_mul_f32_e32 v164, v110, v164
	v_mul_f32_e32 v165, v111, v165
	v_mul_f32_e32 v166, v112, v166
	v_mul_f32_e32 v167, v113, v167
	v_cvt_pk_bf16_f32 v128, v160, v161
	v_cvt_pk_bf16_f32 v129, v162, v163
	v_cvt_pk_bf16_f32 v130, v164, v165
	v_cvt_pk_bf16_f32 v131, v166, v167
	global_store_dwordx4 v154, v[128:131], s[12:13]
	s_add_u32 s14, s14, s17
	s_cmp_ge_u32 s14, 0x8000
	s_cbranch_scc1 .Lkn_st_end
	v_lshlrev_b32_e32 v160, 16, v132
	v_and_b32_e32 v161, 0xffff0000, v132
	v_lshlrev_b32_e32 v162, 16, v133
	v_and_b32_e32 v163, 0xffff0000, v133
	v_lshlrev_b32_e32 v164, 16, v134
	v_and_b32_e32 v165, 0xffff0000, v134
	v_lshlrev_b32_e32 v166, 16, v135
	v_and_b32_e32 v167, 0xffff0000, v135
	v_pk_mul_f32 v[168:169], v[160:161], v[160:161]
	v_pk_mul_f32 v[170:171], v[162:163], v[162:163]
	v_pk_mul_f32 v[172:173], v[164:165], v[164:165]
	v_pk_mul_f32 v[174:175], v[166:167], v[166:167]
	v_add_f32_e32 v168, v168, v169
	v_add_f32_e32 v168, v170, v168
	v_add_f32_e32 v168, v171, v168
	v_add_f32_e32 v168, v172, v168
	v_add_f32_e32 v168, v173, v168
	v_add_f32_e32 v168, v174, v168
	v_add_f32_e32 v168, v175, v168
	s_nop 1
	v_add_f32_dpp v168, v168, v168 quad_perm:[1,0,3,2] row_mask:0xf bank_mask:0xf
	s_nop 1
	v_add_f32_dpp v168, v168, v168 quad_perm:[2,3,0,1] row_mask:0xf bank_mask:0xf
	s_nop 1
	v_mov_b32_dpp v169, v168 row_half_mirror row_mask:0xf bank_mask:0xf
	v_add_f32_e32 v168, v168, v169
	v_fmamk_f32 v168, v168, 0x3c800000, v114
	v_rsq_f32_e32 v168, v168
	s_nop 0
	v_mul_f32_e32 v160, v168, v160
	v_mul_f32_e32 v161, v168, v161
	v_mul_f32_e32 v162, v168, v162
	v_mul_f32_e32 v163, v168, v163
	v_mul_f32_e32 v164, v168, v164
	v_mul_f32_e32 v165, v168, v165
	v_mul_f32_e32 v166, v168, v166
	v_mul_f32_e32 v167, v168, v167
	v_mul_f32_e32 v160, v106, v160
	v_mul_f32_e32 v161, v107, v161
	v_mul_f32_e32 v162, v108, v162
	v_mul_f32_e32 v163, v109, v163
	v_mul_f32_e32 v164, v110, v164
	v_mul_f32_e32 v165, v111, v165
	v_mul_f32_e32 v166, v112, v166
	v_mul_f32_e32 v167, v113, v167
	v_cvt_pk_bf16_f32 v132, v160, v161
	v_cvt_pk_bf16_f32 v133, v162, v163
	v_cvt_pk_bf16_f32 v134, v164, v165
	v_cvt_pk_bf16_f32 v135, v166, v167
	global_store_dwordx4 v155, v[132:135], s[12:13]
	s_add_u32 s14, s14, s17
	s_cmp_ge_u32 s14, 0x8000
	s_cbranch_scc1 .Lkn_st_end
	v_lshlrev_b32_e32 v160, 16, v136
	v_and_b32_e32 v161, 0xffff0000, v136
	v_lshlrev_b32_e32 v162, 16, v137
	v_and_b32_e32 v163, 0xffff0000, v137
	v_lshlrev_b32_e32 v164, 16, v138
	v_and_b32_e32 v165, 0xffff0000, v138
	v_lshlrev_b32_e32 v166, 16, v139
	v_and_b32_e32 v167, 0xffff0000, v139
	v_pk_mul_f32 v[168:169], v[160:161], v[160:161]
	v_pk_mul_f32 v[170:171], v[162:163], v[162:163]
	v_pk_mul_f32 v[172:173], v[164:165], v[164:165]
	v_pk_mul_f32 v[174:175], v[166:167], v[166:167]
	v_add_f32_e32 v168, v168, v169
	v_add_f32_e32 v168, v170, v168
	v_add_f32_e32 v168, v171, v168
	v_add_f32_e32 v168, v172, v168
	v_add_f32_e32 v168, v173, v168
	v_add_f32_e32 v168, v174, v168
	v_add_f32_e32 v168, v175, v168
	s_nop 1
	v_add_f32_dpp v168, v168, v168 quad_perm:[1,0,3,2] row_mask:0xf bank_mask:0xf
	s_nop 1
	v_add_f32_dpp v168, v168, v168 quad_perm:[2,3,0,1] row_mask:0xf bank_mask:0xf
	s_nop 1
	v_mov_b32_dpp v169, v168 row_half_mirror row_mask:0xf bank_mask:0xf
	v_add_f32_e32 v168, v168, v169
	v_fmamk_f32 v168, v168, 0x3c800000, v114
	v_rsq_f32_e32 v168, v168
	s_nop 0
	v_mul_f32_e32 v160, v168, v160
	v_mul_f32_e32 v161, v168, v161
	v_mul_f32_e32 v162, v168, v162
	v_mul_f32_e32 v163, v168, v163
	v_mul_f32_e32 v164, v168, v164
	v_mul_f32_e32 v165, v168, v165
	v_mul_f32_e32 v166, v168, v166
	v_mul_f32_e32 v167, v168, v167
	v_mul_f32_e32 v160, v106, v160
	v_mul_f32_e32 v161, v107, v161
	v_mul_f32_e32 v162, v108, v162
	v_mul_f32_e32 v163, v109, v163
	v_mul_f32_e32 v164, v110, v164
	v_mul_f32_e32 v165, v111, v165
	v_mul_f32_e32 v166, v112, v166
	v_mul_f32_e32 v167, v113, v167
	v_cvt_pk_bf16_f32 v136, v160, v161
	v_cvt_pk_bf16_f32 v137, v162, v163
	v_cvt_pk_bf16_f32 v138, v164, v165
	v_cvt_pk_bf16_f32 v139, v166, v167
	global_store_dwordx4 v156, v[136:139], s[12:13]
	s_add_u32 s14, s14, s17
	s_cmp_ge_u32 s14, 0x8000
	s_cbranch_scc1 .Lkn_st_end
	v_lshlrev_b32_e32 v160, 16, v140
	v_and_b32_e32 v161, 0xffff0000, v140
	v_lshlrev_b32_e32 v162, 16, v141
	v_and_b32_e32 v163, 0xffff0000, v141
	v_lshlrev_b32_e32 v164, 16, v142
	v_and_b32_e32 v165, 0xffff0000, v142
	v_lshlrev_b32_e32 v166, 16, v143
	v_and_b32_e32 v167, 0xffff0000, v143
	v_pk_mul_f32 v[168:169], v[160:161], v[160:161]
	v_pk_mul_f32 v[170:171], v[162:163], v[162:163]
	v_pk_mul_f32 v[172:173], v[164:165], v[164:165]
	v_pk_mul_f32 v[174:175], v[166:167], v[166:167]
	v_add_f32_e32 v168, v168, v169
	v_add_f32_e32 v168, v170, v168
	v_add_f32_e32 v168, v171, v168
	v_add_f32_e32 v168, v172, v168
	v_add_f32_e32 v168, v173, v168
	v_add_f32_e32 v168, v174, v168
	v_add_f32_e32 v168, v175, v168
	s_nop 1
	v_add_f32_dpp v168, v168, v168 quad_perm:[1,0,3,2] row_mask:0xf bank_mask:0xf
	s_nop 1
	v_add_f32_dpp v168, v168, v168 quad_perm:[2,3,0,1] row_mask:0xf bank_mask:0xf
	s_nop 1
	v_mov_b32_dpp v169, v168 row_half_mirror row_mask:0xf bank_mask:0xf
	v_add_f32_e32 v168, v168, v169
	v_fmamk_f32 v168, v168, 0x3c800000, v114
	v_rsq_f32_e32 v168, v168
	s_nop 0
	v_mul_f32_e32 v160, v168, v160
	v_mul_f32_e32 v161, v168, v161
	v_mul_f32_e32 v162, v168, v162
	v_mul_f32_e32 v163, v168, v163
	v_mul_f32_e32 v164, v168, v164
	v_mul_f32_e32 v165, v168, v165
	v_mul_f32_e32 v166, v168, v166
	v_mul_f32_e32 v167, v168, v167
	v_mul_f32_e32 v160, v106, v160
	v_mul_f32_e32 v161, v107, v161
	v_mul_f32_e32 v162, v108, v162
	v_mul_f32_e32 v163, v109, v163
	v_mul_f32_e32 v164, v110, v164
	v_mul_f32_e32 v165, v111, v165
	v_mul_f32_e32 v166, v112, v166
	v_mul_f32_e32 v167, v113, v167
	v_cvt_pk_bf16_f32 v140, v160, v161
	v_cvt_pk_bf16_f32 v141, v162, v163
	v_cvt_pk_bf16_f32 v142, v164, v165
	v_cvt_pk_bf16_f32 v143, v166, v167
	global_store_dwordx4 v157, v[140:143], s[12:13]
	s_add_u32 s14, s14, s17
	s_cmp_ge_u32 s14, 0x8000
	s_cbranch_scc1 .Lkn_st_end
	v_lshlrev_b32_e32 v160, 16, v144
	v_and_b32_e32 v161, 0xffff0000, v144
	v_lshlrev_b32_e32 v162, 16, v145
	v_and_b32_e32 v163, 0xffff0000, v145
	v_lshlrev_b32_e32 v164, 16, v146
	v_and_b32_e32 v165, 0xffff0000, v146
	v_lshlrev_b32_e32 v166, 16, v147
	v_and_b32_e32 v167, 0xffff0000, v147
	v_pk_mul_f32 v[168:169], v[160:161], v[160:161]
	v_pk_mul_f32 v[170:171], v[162:163], v[162:163]
	v_pk_mul_f32 v[172:173], v[164:165], v[164:165]
	v_pk_mul_f32 v[174:175], v[166:167], v[166:167]
	v_add_f32_e32 v168, v168, v169
	v_add_f32_e32 v168, v170, v168
	v_add_f32_e32 v168, v171, v168
	v_add_f32_e32 v168, v172, v168
	v_add_f32_e32 v168, v173, v168
	v_add_f32_e32 v168, v174, v168
	v_add_f32_e32 v168, v175, v168
	s_nop 1
	v_add_f32_dpp v168, v168, v168 quad_perm:[1,0,3,2] row_mask:0xf bank_mask:0xf
	s_nop 1
	v_add_f32_dpp v168, v168, v168 quad_perm:[2,3,0,1] row_mask:0xf bank_mask:0xf
	s_nop 1
	v_mov_b32_dpp v169, v168 row_half_mirror row_mask:0xf bank_mask:0xf
	v_add_f32_e32 v168, v168, v169
	v_fmamk_f32 v168, v168, 0x3c800000, v114
	v_rsq_f32_e32 v168, v168
	s_nop 0
	v_mul_f32_e32 v160, v168, v160
	v_mul_f32_e32 v161, v168, v161
	v_mul_f32_e32 v162, v168, v162
	v_mul_f32_e32 v163, v168, v163
	v_mul_f32_e32 v164, v168, v164
	v_mul_f32_e32 v165, v168, v165
	v_mul_f32_e32 v166, v168, v166
	v_mul_f32_e32 v167, v168, v167
	v_mul_f32_e32 v160, v106, v160
	v_mul_f32_e32 v161, v107, v161
	v_mul_f32_e32 v162, v108, v162
	v_mul_f32_e32 v163, v109, v163
	v_mul_f32_e32 v164, v110, v164
	v_mul_f32_e32 v165, v111, v165
	v_mul_f32_e32 v166, v112, v166
	v_mul_f32_e32 v167, v113, v167
	v_cvt_pk_bf16_f32 v144, v160, v161
	v_cvt_pk_bf16_f32 v145, v162, v163
	v_cvt_pk_bf16_f32 v146, v164, v165
	v_cvt_pk_bf16_f32 v147, v166, v167
	global_store_dwordx4 v158, v[144:147], s[12:13]
	s_add_u32 s14, s14, s17
	s_cmp_ge_u32 s14, 0x8000
	s_cbranch_scc1 .Lkn_st_end
	v_lshlrev_b32_e32 v160, 16, v148
	v_and_b32_e32 v161, 0xffff0000, v148
	v_lshlrev_b32_e32 v162, 16, v149
	v_and_b32_e32 v163, 0xffff0000, v149
	v_lshlrev_b32_e32 v164, 16, v150
	v_and_b32_e32 v165, 0xffff0000, v150
	v_lshlrev_b32_e32 v166, 16, v151
	v_and_b32_e32 v167, 0xffff0000, v151
	v_pk_mul_f32 v[168:169], v[160:161], v[160:161]
	v_pk_mul_f32 v[170:171], v[162:163], v[162:163]
	v_pk_mul_f32 v[172:173], v[164:165], v[164:165]
	v_pk_mul_f32 v[174:175], v[166:167], v[166:167]
	v_add_f32_e32 v168, v168, v169
	v_add_f32_e32 v168, v170, v168
	v_add_f32_e32 v168, v171, v168
	v_add_f32_e32 v168, v172, v168
	v_add_f32_e32 v168, v173, v168
	v_add_f32_e32 v168, v174, v168
	v_add_f32_e32 v168, v175, v168
	s_nop 1
	v_add_f32_dpp v168, v168, v168 quad_perm:[1,0,3,2] row_mask:0xf bank_mask:0xf
	s_nop 1
	v_add_f32_dpp v168, v168, v168 quad_perm:[2,3,0,1] row_mask:0xf bank_mask:0xf
	s_nop 1
	v_mov_b32_dpp v169, v168 row_half_mirror row_mask:0xf bank_mask:0xf
	v_add_f32_e32 v168, v168, v169
	v_fmamk_f32 v168, v168, 0x3c800000, v114
	v_rsq_f32_e32 v168, v168
	s_nop 0
	v_mul_f32_e32 v160, v168, v160
	v_mul_f32_e32 v161, v168, v161
	v_mul_f32_e32 v162, v168, v162
	v_mul_f32_e32 v163, v168, v163
	v_mul_f32_e32 v164, v168, v164
	v_mul_f32_e32 v165, v168, v165
	v_mul_f32_e32 v166, v168, v166
	v_mul_f32_e32 v167, v168, v167
	v_mul_f32_e32 v160, v106, v160
	v_mul_f32_e32 v161, v107, v161
	v_mul_f32_e32 v162, v108, v162
	v_mul_f32_e32 v163, v109, v163
	v_mul_f32_e32 v164, v110, v164
	v_mul_f32_e32 v165, v111, v165
	v_mul_f32_e32 v166, v112, v166
	v_mul_f32_e32 v167, v113, v167
	v_cvt_pk_bf16_f32 v148, v160, v161
	v_cvt_pk_bf16_f32 v149, v162, v163
	v_cvt_pk_bf16_f32 v150, v164, v165
	v_cvt_pk_bf16_f32 v151, v166, v167
	global_store_dwordx4 v159, v[148:151], s[12:13]
	s_add_u32 s14, s14, s17
.Lkn_st_end:
	s_lshl_b32 s15, s17, 3
	s_add_u32 s16, s16, s15
	s_branch .Lkn_loop
.Lkn_done:
	v_readfirstlane_b32 s4, v2
	s_ashr_i32 s0, s4, 6
	s_add_i32 s0, s97, s0
	s_add_i32 s2, s0, 0x8000
	s_cmp_gt_i32 s2, 0x83ff
	s_cbranch_scc1 .LBB0_715
	v_and_b32_e32 v3, 63, v2
	v_readlane_b32 s8, v253, 60
	v_lshlrev_b32_e32 v4, 2, v3
	v_readlane_b32 s9, v253, 61
	v_readlane_b32 s10, v253, 62
	v_readlane_b32 s11, v253, 63
	v_readlane_b32 s12, v254, 0
	v_readlane_b32 s13, v254, 1
	v_readlane_b32 s14, v254, 2
	v_readlane_b32 s15, v254, 3
	v_readlane_b32 s16, v254, 4
	v_readlane_b32 s17, v254, 5
	v_readlane_b32 s18, v254, 6
	v_readlane_b32 s19, v254, 7
	v_readlane_b32 s20, v254, 8
	v_readlane_b32 s21, v254, 9
	v_readlane_b32 s22, v254, 10
	v_readlane_b32 s23, v254, 11
	v_mov_b32_e32 v25, 0x600
	v_mov_b32_e32 v26, 0x358637bd
	s_nop 2
	global_load_dword v16, v4, s[22:23]
	v_and_b32_e32 v4, 31, v2
	v_readlane_b32 s8, v253, 40
	v_lshlrev_b32_e32 v4, 2, v4
	v_readlane_b32 s10, v253, 42
	v_readlane_b32 s11, v253, 43
	v_readlane_b32 s12, v253, 44
	v_readlane_b32 s13, v253, 45
	v_readlane_b32 s14, v253, 46
	v_readlane_b32 s15, v253, 47
	v_readlane_b32 s16, v253, 48
	global_load_dword v17, v4, s[10:11]
	v_mbcnt_hi_u32_b32 v4, -1, v1
	v_and_b32_e32 v5, 64, v4
	v_add_u32_e32 v5, 64, v5
	v_xor_b32_e32 v6, 32, v4
	v_cmp_lt_i32_e32 vcc, v6, v5
	v_readlane_b32 s17, v253, 49
	v_readlane_b32 s18, v253, 50
	v_cndmask_b32_e32 v6, v4, v6, vcc
	v_lshlrev_b32_e32 v18, 2, v6
	v_xor_b32_e32 v6, 16, v4
	v_cmp_lt_i32_e32 vcc, v6, v5
	v_readlane_b32 s19, v253, 51
	v_readlane_b32 s20, v253, 52
	v_cndmask_b32_e32 v6, v4, v6, vcc
	v_lshlrev_b32_e32 v19, 2, v6
	v_xor_b32_e32 v6, 8, v4
	v_cmp_lt_i32_e32 vcc, v6, v5
	v_readlane_b32 s21, v253, 53
	v_readlane_b32 s22, v253, 54
	v_cndmask_b32_e32 v6, v4, v6, vcc
	v_lshlrev_b32_e32 v20, 2, v6
	v_xor_b32_e32 v6, 4, v4
	v_cmp_lt_i32_e32 vcc, v6, v5
	v_readlane_b32 s23, v253, 55
	v_readlane_b32 s12, v254, 28
	v_cndmask_b32_e32 v6, v4, v6, vcc
	v_lshlrev_b32_e32 v21, 2, v6
	v_xor_b32_e32 v6, 2, v4
	v_cmp_lt_i32_e32 vcc, v6, v5
	v_and_b32_e32 v2, 16, v2
	s_bfe_u32 s10, s4, 0x30006
	v_cndmask_b32_e32 v6, v4, v6, vcc
	v_lshlrev_b32_e32 v22, 2, v6
	v_xor_b32_e32 v6, 1, v4
	v_cmp_lt_i32_e32 vcc, v6, v5
	v_mov_b32_e32 v5, 0
	v_readlane_b32 s22, v254, 38
	v_cndmask_b32_e32 v4, v4, v6, vcc
	v_lshlrev_b32_e32 v23, 2, v4
	v_lshlrev_b32_e32 v4, 1, v3
	v_readlane_b32 s23, v254, 39
	v_readlane_b32 s26, v254, 42
	v_readlane_b32 s27, v254, 43
	v_cmp_gt_u32_e32 vcc, 32, v3
	v_and_b32_e32 v24, 30, v4
	v_cmp_eq_u32_e64 s[0:1], 0, v2
	s_bitset1_b32 s10, 11
	v_lshl_add_u64 v[2:3], s[22:23], 0, v[4:5]
	v_lshl_add_u64 v[4:5], s[26:27], 0, v[4:5]
	s_mov_b32 s11, 0x800000
	v_readlane_b32 s9, v253, 41
	v_readlane_b32 s13, v254, 29
	v_readlane_b32 s14, v254, 30
	v_readlane_b32 s15, v254, 31
	v_readlane_b32 s16, v254, 32
	v_readlane_b32 s17, v254, 33
	v_readlane_b32 s18, v254, 34
	v_readlane_b32 s19, v254, 35
	v_readlane_b32 s20, v254, 36
	v_readlane_b32 s21, v254, 37
	v_readlane_b32 s24, v254, 40
	v_readlane_b32 s25, v254, 41
	s_branch .LBB0_709

.LBB0_859:
	s_or_b64 exec, exec, s[4:5]
	v_pk_mul_f32 v[20:21], v[16:17], v[20:21] op_sel_hi:[0,1]
	v_pk_mul_f32 v[18:19], v[16:17], v[18:19] op_sel_hi:[0,1]
	s_waitcnt vmcnt(0)
	v_pk_mul_f32 v[20:21], v[10:11], v[20:21]
	v_pk_mul_f32 v[22:23], v[16:17], v[22:23] op_sel_hi:[0,1]
	v_pk_mul_f32 v[16:17], v[16:17], v[24:25] op_sel_hi:[0,1]
	v_pk_mul_f32 v[24:25], v[6:7], v[16:17]
	v_cvt_pk_bf16_f32 v17, v20, v21
	v_lshlrev_b32_e32 v20, 2, v166
	v_and_b32_e32 v20, 12, v20
	v_bfe_u32 v21, v166, 2, 2
	v_bitop3_b32 v20, v20, v45, v21 bitop3:0x36
	v_pk_mul_f32 v[18:19], v[8:9], v[18:19]
	v_pk_mul_f32 v[22:23], v[4:5], v[22:23]
	v_lshlrev_b32_e32 v199, 8, v166
	v_lshlrev_b32_e32 v201, 4, v20
	v_cvt_pk_bf16_f32 v16, v18, v19
	v_cvt_pk_bf16_f32 v18, v22, v23
	v_cvt_pk_bf16_f32 v19, v24, v25
	v_add3_u32 v20, 0, v201, v199
	ds_write_b128 v20, v[116:119]
	v_and_b32_e32 v19, 0xffff0000, v120
	v_lshlrev_b32_e32 v18, 16, v120
	v_pk_mul_f32 v[16:17], v[18:19], v[18:19]
	v_and_b32_e32 v21, 0xffff0000, v121
	v_lshlrev_b32_e32 v20, 16, v121
	v_pk_mul_f32 v[52:53], v[20:21], v[20:21]
	v_add_f32_e32 v16, v16, v17
	v_and_b32_e32 v23, 0xffff0000, v122
	v_lshlrev_b32_e32 v22, 16, v122
	v_add_f32_e32 v16, v52, v16
	v_pk_mul_f32 v[56:57], v[22:23], v[22:23]
	v_add_f32_e32 v16, v53, v16
	v_and_b32_e32 v25, 0xffff0000, v123
	v_lshlrev_b32_e32 v24, 16, v123
	v_add_f32_e32 v16, v56, v16
	v_pk_mul_f32 v[64:65], v[24:25], v[24:25]
	v_add_f32_e32 v16, v57, v16
	v_add_f32_e32 v16, v64, v16
	v_add_f32_e32 v16, v65, v16
	ds_bpermute_b32 v17, v196, v16
	s_waitcnt lgkmcnt(2)
	v_mov_b32_e32 v26, 1.0
	s_waitcnt lgkmcnt(0)
	v_add_f32_e32 v16, v16, v17
	ds_bpermute_b32 v17, v197, v16
	s_waitcnt lgkmcnt(0)
	v_add_f32_e32 v17, v16, v17
	ds_bpermute_b32 v49, v198, v17
	v_mov_b32_e32 v16, 1.0
	s_and_saveexec_b64 s[4:5], s[0:1]
	s_cbranch_execz .LBB0_861
	s_waitcnt lgkmcnt(0)
	v_add_f32_e32 v17, v17, v49
	v_fmamk_f32 v17, v17, 0x3c800000, v160
	v_mul_f32_e32 v26, 0x4b800000, v17
	v_cmp_gt_f32_e32 vcc, s10, v17
	s_nop 1
	v_cndmask_b32_e32 v17, v17, v26, vcc
	v_rsq_f32_e32 v17, v17
	s_nop 0
	v_mul_f32_e32 v26, 0x45800000, v17
	v_cndmask_b32_e32 v26, v17, v26, vcc
.LBB0_861:
	s_or_b64 exec, exec, s[4:5]
	v_pk_mul_f32 v[18:19], v[26:27], v[18:19] op_sel_hi:[0,1]
	v_pk_mul_f32 v[20:21], v[26:27], v[20:21] op_sel_hi:[0,1]
	v_pk_mul_f32 v[22:23], v[26:27], v[22:23] op_sel_hi:[0,1]
	v_pk_mul_f32 v[18:19], v[8:9], v[18:19]
	v_pk_mul_f32 v[20:21], v[10:11], v[20:21]
	v_pk_mul_f32 v[22:23], v[4:5], v[22:23]
	v_lshlrev_b32_e32 v17, 2, v168
	v_cvt_pk_bf16_f32 v18, v18, v19
	v_cvt_pk_bf16_f32 v19, v20, v21
	v_cvt_pk_bf16_f32 v20, v22, v23
	v_and_b32_e32 v17, 12, v17
	v_bfe_u32 v22, v168, 2, 2
	v_pk_mul_f32 v[24:25], v[26:27], v[24:25] op_sel_hi:[0,1]
	v_bitop3_b32 v17, v17, v45, v22 bitop3:0x36
	v_pk_mul_f32 v[24:25], v[6:7], v[24:25]
	v_lshlrev_b32_e32 v202, 8, v168
	v_lshlrev_b32_e32 v203, 4, v17
	v_cvt_pk_bf16_f32 v21, v24, v25
	v_add3_u32 v17, 0, v203, v202
	ds_write_b128 v17, v[120:123]
	v_and_b32_e32 v19, 0xffff0000, v124
	v_lshlrev_b32_e32 v18, 16, v124
	v_pk_mul_f32 v[52:53], v[18:19], v[18:19]
	v_and_b32_e32 v21, 0xffff0000, v125
	v_lshlrev_b32_e32 v20, 16, v125
	v_pk_mul_f32 v[56:57], v[20:21], v[20:21]
	v_add_f32_e32 v17, v52, v53
	v_and_b32_e32 v23, 0xffff0000, v126
	v_lshlrev_b32_e32 v22, 16, v126
	v_add_f32_e32 v17, v56, v17
	v_pk_mul_f32 v[64:65], v[22:23], v[22:23]
	v_add_f32_e32 v17, v57, v17
	v_and_b32_e32 v25, 0xffff0000, v127
	v_lshlrev_b32_e32 v24, 16, v127
	v_add_f32_e32 v17, v64, v17
	v_pk_mul_f32 v[66:67], v[24:25], v[24:25]
	v_add_f32_e32 v17, v65, v17
	v_add_f32_e32 v17, v66, v17
	v_add_f32_e32 v17, v67, v17
	ds_bpermute_b32 v26, v196, v17
	s_waitcnt lgkmcnt(0)
	v_add_f32_e32 v17, v17, v26
	ds_bpermute_b32 v26, v197, v17
	s_waitcnt lgkmcnt(0)
	v_add_f32_e32 v17, v17, v26
	ds_bpermute_b32 v26, v198, v17
	s_and_saveexec_b64 s[4:5], s[0:1]
	s_cbranch_execz .LBB0_863
	s_waitcnt lgkmcnt(0)
	v_add_f32_e32 v16, v17, v26
	v_fmamk_f32 v16, v16, 0x3c800000, v160
	v_mul_f32_e32 v17, 0x4b800000, v16
	v_cmp_gt_f32_e32 vcc, s10, v16
	s_nop 1
	v_cndmask_b32_e32 v16, v16, v17, vcc
	v_rsq_f32_e32 v16, v16
	s_nop 0
	v_mul_f32_e32 v17, 0x45800000, v16
	v_cndmask_b32_e32 v16, v16, v17, vcc
.LBB0_863:
	s_or_b64 exec, exec, s[4:5]
	v_pk_mul_f32 v[20:21], v[16:17], v[20:21] op_sel_hi:[0,1]
	v_pk_mul_f32 v[18:19], v[16:17], v[18:19] op_sel_hi:[0,1]
	v_pk_mul_f32 v[20:21], v[10:11], v[20:21]
	v_pk_mul_f32 v[22:23], v[16:17], v[22:23] op_sel_hi:[0,1]
	v_pk_mul_f32 v[16:17], v[16:17], v[24:25] op_sel_hi:[0,1]
	v_pk_mul_f32 v[24:25], v[6:7], v[16:17]
	v_cvt_pk_bf16_f32 v17, v20, v21
	v_lshlrev_b32_e32 v20, 2, v170
	v_and_b32_e32 v20, 12, v20
	v_bfe_u32 v21, v170, 2, 2
	v_bitop3_b32 v20, v20, v45, v21 bitop3:0x36
	v_pk_mul_f32 v[18:19], v[8:9], v[18:19]
	v_pk_mul_f32 v[22:23], v[4:5], v[22:23]
	v_lshlrev_b32_e32 v204, 8, v170
	v_lshlrev_b32_e32 v205, 4, v20
	v_cvt_pk_bf16_f32 v16, v18, v19
	v_cvt_pk_bf16_f32 v18, v22, v23
	v_cvt_pk_bf16_f32 v19, v24, v25
	v_add3_u32 v20, 0, v205, v204
	ds_write_b128 v20, v[124:127]
	v_and_b32_e32 v17, 0xffff0000, v128
	v_lshlrev_b32_e32 v16, 16, v128
	v_pk_mul_f32 v[24:25], v[16:17], v[16:17]
	v_and_b32_e32 v19, 0xffff0000, v129
	v_lshlrev_b32_e32 v18, 16, v129
	v_pk_mul_f32 v[52:53], v[18:19], v[18:19]
	v_add_f32_e32 v24, v24, v25
	v_and_b32_e32 v21, 0xffff0000, v130
	v_lshlrev_b32_e32 v20, 16, v130
	v_add_f32_e32 v24, v52, v24
	v_pk_mul_f32 v[56:57], v[20:21], v[20:21]
	v_add_f32_e32 v24, v53, v24
	v_and_b32_e32 v23, 0xffff0000, v131
	v_lshlrev_b32_e32 v22, 16, v131
	v_add_f32_e32 v24, v56, v24
	v_pk_mul_f32 v[64:65], v[22:23], v[22:23]
	v_add_f32_e32 v24, v57, v24
	v_add_f32_e32 v24, v64, v24
	v_add_f32_e32 v24, v65, v24
	ds_bpermute_b32 v25, v196, v24
	s_sub_i32 s21, 0, s8
	s_lshl_b32 s12, s9, 7
	s_waitcnt lgkmcnt(0)
	v_add_f32_e32 v24, v24, v25
	ds_bpermute_b32 v25, v197, v24
	s_waitcnt lgkmcnt(0)
	v_add_f32_e32 v25, v24, v25
	ds_bpermute_b32 v26, v198, v25
	v_mov_b32_e32 v24, 1.0
	s_and_saveexec_b64 s[4:5], s[0:1]
	s_cbranch_execz .LBB0_865
	s_waitcnt lgkmcnt(0)
	v_add_f32_e32 v24, v25, v26
	v_fmamk_f32 v24, v24, 0x3c800000, v160
	v_mul_f32_e32 v25, 0x4b800000, v24
	v_cmp_gt_f32_e32 vcc, s10, v24
	s_nop 1
	v_cndmask_b32_e32 v24, v24, v25, vcc
	v_rsq_f32_e32 v24, v24
	s_nop 0
	v_mul_f32_e32 v25, 0x45800000, v24
	v_cndmask_b32_e32 v24, v24, v25, vcc
.LBB0_865:
	s_or_b64 exec, exec, s[4:5]
	v_add_f32_e32 v44, v44, v48
	v_mul_f32_e32 v48, 0x4f800000, v44
	v_cmp_gt_f32_e32 vcc, s11, v44
	v_add_f32_e32 v46, v46, v47
	v_and_b32_e32 v25, 63, v59
	v_cndmask_b32_e32 v44, v44, v48, vcc
	v_sqrt_f32_e32 v48, v44
	v_lshlrev_b32_e32 v218, 8, v172
	s_lshl_b32 s25, s21, 1
	s_movk_i32 s4, 0x50
	v_add_u32_e32 v47, -1, v48
	v_fma_f32 v65, -v47, v48, v44
	v_cmp_ge_f32_e64 s[8:9], 0, v65
	v_add_u32_e32 v65, 1, v48
	v_readlane_b32 s36, v254, 28
	v_cndmask_b32_e64 v47, v48, v47, s[8:9]
	v_fma_f32 v48, -v65, v48, v44
	v_cmp_lt_f32_e64 s[8:9], 0, v48
	v_lshrrev_b32_e32 v61, 16, v38
	s_add_i32 s25, s25, 16
	v_cndmask_b32_e64 v47, v47, v65, s[8:9]
	v_mul_f32_e32 v48, 0x37800000, v47
	v_cndmask_b32_e32 v47, v47, v48, vcc
	v_mul_f32_e32 v48, 0x4f800000, v46
	v_cmp_gt_f32_e32 vcc, s11, v46
	v_cmp_class_f32_e64 s[8:9], v44, v192
	s_bitset1_b32 s18, 7
	v_cndmask_b32_e32 v46, v46, v48, vcc
	v_sqrt_f32_e32 v48, v46
	v_cndmask_b32_e64 v44, v47, v44, s[8:9]
	v_mul_f32_e32 v44, 0x41000000, v44
	s_or_b32 s26, s24, 31
	v_add_u32_e32 v47, -1, v48
	v_fma_f32 v65, -v47, v48, v46
	v_cmp_ge_f32_e64 s[8:9], 0, v65
	v_add_u32_e32 v65, 1, v48
	v_readlane_b32 s48, v254, 40
	v_cndmask_b32_e64 v47, v48, v47, s[8:9]
	v_fma_f32 v48, -v65, v48, v46
	v_cmp_lt_f32_e64 s[8:9], 0, v48
	v_perm_b32 v156, v61, v38, s22
	v_readlane_b32 s37, v254, 29
	v_cndmask_b32_e64 v47, v47, v65, s[8:9]
	v_mul_f32_e32 v48, 0x37800000, v47
	v_cndmask_b32_e32 v47, v47, v48, vcc
	v_cmp_class_f32_e32 vcc, v46, v192
	v_bfe_u32 v48, v59, 1, 1
	v_readlane_b32 s38, v254, 30
	v_cndmask_b32_e32 v46, v47, v46, vcc
	v_mul_f32_e32 v46, 0x40b504f3, v46
	v_mul_f32_e32 v15, v15, v46
	v_fmac_f32_e32 v15, v14, v44
	v_lshlrev_b32_e32 v14, 2, v55
	v_and_b32_e32 v14, 12, v14
	v_bfe_u32 v44, v59, 2, 2
	v_bitop3_b32 v46, v14, v51, v44 bitop3:0x36
	v_lshlrev_b32_e32 v207, 4, v46
	v_or_b32_e32 v46, 2, v51
	v_bitop3_b32 v46, v14, v46, v44 bitop3:0x36
	v_lshlrev_b32_e32 v208, 4, v46
	v_or_b32_e32 v46, 4, v51
	v_bitop3_b32 v46, v14, v46, v44 bitop3:0x36
	v_lshlrev_b32_e32 v209, 4, v46
	v_or_b32_e32 v46, 6, v51
	v_bitop3_b32 v14, v14, v46, v44 bitop3:0x36
	v_lshlrev_b32_e32 v210, 4, v14
	v_lshrrev_b32_e32 v14, 3, v25
	v_fmamk_f32 v46, v15, 0x3f828f5c, v193
	v_and_b32_e32 v15, 4, v14
	v_or_b32_e32 v47, v15, v44
	v_and_or_b32 v14, v14, 2, v48
	v_lshlrev_b32_e32 v25, 3, v25
	v_or_b32_e32 v15, 8, v15
	v_or_b32_e32 v48, 8, v14
	v_lshlrev_b32_e32 v211, 8, v47
	v_and_b32_e32 v47, 12, v59
	v_and_b32_e32 v213, 8, v25
	v_or_b32_e32 v25, v15, v44
	v_lshrrev_b32_e32 v15, 2, v15
	v_or_b32_e32 v59, v51, v47
	v_lshlrev_b32_e32 v214, 8, v25
	v_bitop3_b32 v25, v15, v48, v47 bitop3:0x36
	v_bitop3_b32 v65, v14, v59, 8 bitop3:0x36
	v_lshlrev_b32_e32 v215, 4, v25
	v_or_b32_e32 v25, 12, v14
	v_bitop3_b32 v14, v14, v59, 12 bitop3:0x36
	v_lshlrev_b32_e32 v216, 4, v14
	v_bitop3_b32 v14, v15, v25, v47 bitop3:0x36
	v_lshlrev_b32_e32 v217, 4, v14
	v_pk_mul_f32 v[14:15], v[24:25], v[16:17] op_sel_hi:[0,1]
	v_pk_mul_f32 v[8:9], v[8:9], v[14:15]
	v_pk_mul_f32 v[14:15], v[24:25], v[18:19] op_sel_hi:[0,1]
	v_pk_mul_f32 v[10:11], v[10:11], v[14:15]
	v_pk_mul_f32 v[14:15], v[24:25], v[20:21] op_sel_hi:[0,1]
	v_pk_mul_f32 v[14:15], v[4:5], v[14:15]
	v_pk_mul_f32 v[4:5], v[24:25], v[22:23] op_sel_hi:[0,1]
	v_pk_mul_f32 v[16:17], v[6:7], v[4:5]
	v_cvt_pk_bf16_f32 v4, v8, v9
	v_lshlrev_b32_e32 v8, 2, v172
	v_and_b32_e32 v8, 12, v8
	v_bfe_u32 v9, v172, 2, 2
	v_bitop3_b32 v8, v8, v45, v9 bitop3:0x36
	v_lshlrev_b32_e32 v219, 4, v8
	v_cvt_pk_bf16_f32 v5, v10, v11
	v_cvt_pk_bf16_f32 v6, v14, v15
	v_cvt_pk_bf16_f32 v7, v16, v17
	v_add3_u32 v8, 0, v219, v218
	ds_write_b128 v8, v[128:131]
	v_mul_lo_u32 v4, v174, s4
	s_lshl_b32 s4, s12, 1
	v_readlane_b32 s39, v254, 31
	v_readlane_b32 s40, v254, 32
	v_readlane_b32 s41, v254, 33
	v_readlane_b32 s42, v254, 34
	v_readlane_b32 s43, v254, 35
	v_readlane_b32 s44, v254, 36
	v_readlane_b32 s45, v254, 37
	v_readlane_b32 s46, v254, 38
	v_readlane_b32 s47, v254, 39
	v_readlane_b32 s49, v254, 41
	v_readlane_b32 s50, v254, 42
	v_readlane_b32 s51, v254, 43
	s_add_u32 s4, s48, s4
	v_mov_b32_e32 v61, v3
	v_lshrrev_b32_e32 v56, 16, v13
	v_add3_u32 v220, s80, v4, v60
	s_addc_u32 s5, s49, 0
	v_lshl_add_u64 v[178:179], s[40:41], 0, v[60:61]
	v_readlane_b32 s36, v253, 40
	v_lshrrev_b32_e32 v49, 16, v30
	v_lshrrev_b32_e32 v50, 16, v31
	v_lshrrev_b32_e32 v57, 16, v36
	v_lshrrev_b32_e32 v58, 16, v37
	v_lshrrev_b32_e32 v63, 16, v40
	v_lshrrev_b32_e32 v64, 16, v41
	ds_write_b128 v220, v[132:135]
	v_mul_u32_u24_e32 v4, 0x50, v55
	v_perm_b32 v152, v56, v13, s22
	v_mov_b32_e32 v13, v3
	v_readlane_b32 s37, v253, 41
	v_mov_b32_e32 v16, v3
	v_mov_b32_e32 v17, v3
	s_waitcnt lgkmcnt(0)
	s_barrier
	v_add3_u32 v222, s80, v4, v62
	v_xor_b32_e32 v20, 0x80000000, v46
	v_perm_b32 v146, v50, v31, s22
	v_perm_b32 v145, v49, v30, s22
	v_perm_b32 v154, v58, v37, s22
	v_perm_b32 v153, v57, v36, s22
	v_perm_b32 v158, v64, v41, s22
	v_perm_b32 v157, v63, v40, s22
	v_bfi_b32 v159, s23, v39, v39
	v_bfi_b32 v139, s23, v43, v43
	v_bfi_b32 v143, s23, v42, v42
	v_lshlrev_b32_e32 v221, 2, v51
	v_lshl_add_u64 v[176:177], s[4:5], 0, v[2:3]
	v_lshl_add_u64 v[180:181], s[36:37], 0, v[12:13]
	v_mov_b32_e32 v240, 1.0
	v_mov_b32_e32 v241, 1.0
	v_mov_b32_e32 v243, 1.0
	v_mov_b32_e32 v252, 1.0
	v_mov_b32_e32 v248, 1.0
	v_mov_b32_e32 v249, 1.0
	v_mov_b32_e32 v250, 1.0
	v_mov_b32_e32 v251, 1.0
	s_mov_b64 vcc, exec
	s_and_b64 exec, exec, s[0:1]
	global_load_dwordx4 v[248:251], v[180:181], off
	global_load_dwordx2 v[240:241], v[180:181], off offset:16
	global_load_dword v243, v[180:181], off offset:24
	global_load_dword v252, v[180:181], off offset:28
	s_mov_b64 exec, vcc
	v_mov_b32_e32 v2, v3
	v_mov_b32_e32 v4, v3
	v_mov_b32_e32 v5, v3
	v_mov_b32_e32 v6, v3
	v_mov_b32_e32 v7, v3
	v_mov_b32_e32 v8, v3
	v_mov_b32_e32 v9, v3
	v_mov_b32_e32 v10, v3
	v_mov_b32_e32 v11, v3
	v_mov_b32_e32 v12, v3
	v_mov_b32_e32 v14, v3
	v_mov_b32_e32 v15, v3
	v_mov_b64_e32 v[50:51], v[16:17]
	s_waitcnt lgkmcnt(2)
	v_lshrrev_b32_e32 v26, 16, v28
	v_lshrrev_b32_e32 v52, 16, v27
	v_lshrrev_b32_e32 v53, 16, v33
	v_lshrrev_b32_e32 v54, 16, v34
	v_mov_b64_e32 v[48:49], v[14:15]
	v_mov_b64_e32 v[46:47], v[12:13]
	v_mov_b64_e32 v[44:45], v[10:11]
	v_mov_b64_e32 v[42:43], v[8:9]
	v_mov_b64_e32 v[40:41], v[6:7]
	v_mov_b64_e32 v[38:39], v[4:5]
	v_mov_b64_e32 v[36:37], v[2:3]
	v_mov_b64_e32 v[18:19], v[16:17]
	s_mov_b32 s20, 0
	v_lshlrev_b32_e32 v206, 8, v55
	v_lshlrev_b32_e32 v212, 4, v65
	v_perm_b32 v144, v26, v28, s22
	v_bfi_b32 v147, s23, v29, v29
	v_perm_b32 v150, v54, v34, s22
	v_perm_b32 v149, v53, v33, s22
	v_perm_b32 v148, v52, v27, s22
	v_bfi_b32 v151, s23, v32, v32
	v_bfi_b32 v155, s23, v35, v35
	v_mov_b32_e32 v21, v20
	v_mov_b32_e32 v22, v20
	v_mov_b32_e32 v23, v20
	v_mov_b32_e32 v24, v20
	v_mov_b32_e32 v25, v20
	v_mov_b32_e32 v26, v20
	v_mov_b32_e32 v27, v20
	v_mov_b32_e32 v28, v20
	v_mov_b32_e32 v29, v20
	v_mov_b32_e32 v30, v20
	v_mov_b32_e32 v31, v20
	v_mov_b32_e32 v32, v20
	v_mov_b32_e32 v33, v20
	v_mov_b32_e32 v34, v20
	v_mov_b32_e32 v35, v20
	v_mov_b32_e32 v223, 0
	s_movk_i32 s27, 0x7f
	v_mov_b64_e32 v[16:17], v[14:15]
	v_mov_b64_e32 v[14:15], v[12:13]
	v_mov_b64_e32 v[12:13], v[10:11]
	v_mov_b64_e32 v[10:11], v[8:9]
	v_mov_b64_e32 v[8:9], v[6:7]
	v_mov_b64_e32 v[6:7], v[4:5]
	v_mov_b64_e32 v[4:5], v[2:3]
	v_readlane_b32 s38, v253, 42
	v_readlane_b32 s39, v253, 43
	v_readlane_b32 s40, v253, 44
	v_readlane_b32 s41, v253, 45
	v_readlane_b32 s42, v253, 46
	v_readlane_b32 s43, v253, 47
	v_readlane_b32 s44, v253, 48
	v_readlane_b32 s45, v253, 49
	v_readlane_b32 s46, v253, 50
	v_readlane_b32 s47, v253, 51
	v_readlane_b32 s48, v253, 52
	v_readlane_b32 s49, v253, 53
	v_readlane_b32 s50, v253, 54
	v_readlane_b32 s51, v253, 55

.LBB0_877:
	s_and_b32 s9, s28, 1
	s_lshl_b32 s4, s9, 15
	s_add_i32 s8, s4, 0
	v_add3_u32 v2, s8, v201, v199
	v_add3_u32 v64, s8, v203, v202
	v_add3_u32 v52, s8, v205, v204
	v_add3_u32 v53, s8, v219, v218
	s_mulk_i32 s9, 0x2800
	v_add_u32_e32 v54, s9, v220
	s_waitcnt vmcnt(0) lgkmcnt(0)
	ds_write_b128 v2, v[116:119]
	ds_write_b128 v64, v[120:123]
	ds_write_b128 v52, v[124:127]
	ds_write_b128 v53, v[128:131]
	ds_write_b128 v54, v[132:135]
